# add touch-prefetch of the residual tile (x / X1B) into cache during late K-loop of P5/P8
# baseline (speedup 1.0000x reference)
.LBB0_529:
	s_cmp_lg_u32 s69, 40
	s_cbranch_scc1 .Ltouch5_skip
	s_cmp_lt_i32 s37, 32
	s_cbranch_scc1 .Ltouch5_ctx
	v_readlane_b32 s98, v249, 11
	v_readlane_b32 s99, v249, 12
	s_sub_i32 s100, s37, 32
	s_branch .Ltouch5_go
.Ltouch5_ctx:
	v_readlane_b32 s98, v249, 9
	v_readlane_b32 s99, v249, 10
	s_mov_b32 s100, s37
.Ltouch5_go:
	s_nop 3
	s_lshl_b32 s100, s100, 22
	s_add_u32 s98, s98, s100
	s_addc_u32 s99, s99, 0
	s_lshl_b32 s100, s72, 10
	s_add_u32 s98, s98, s100
	s_addc_u32 s99, s99, 0
	v_mbcnt_lo_u32_b32 v250, -1, 0
	v_mbcnt_hi_u32_b32 v250, -1, v250
	s_lshr_b32 s100, s73, 10
	v_lshl_or_b32 v250, s100, 6, v250
	v_lshrrev_b32_e32 v251, 3, v250
	v_and_b32_e32 v250, 7, v250
	v_lshlrev_b32_e32 v250, 7, v250
	v_lshl_add_u32 v250, v251, 14, v250
	global_load_dword v251, v250, s[98:99]
	s_add_u32 s98, s98, 0x100000
	s_addc_u32 s99, s99, 0
	global_load_dword v251, v250, s[98:99]
	s_add_u32 s98, s98, 0x100000
	s_addc_u32 s99, s99, 0
	global_load_dword v251, v250, s[98:99]
	s_add_u32 s98, s98, 0x100000
	s_addc_u32 s99, s99, 0
	global_load_dword v251, v250, s[98:99]

.LBB0_904:
	s_cmp_lg_u32 s88, 232
	s_cbranch_scc1 .Ltouch8_skip
	s_mul_i32 s100, s86, 0x208000
	s_add_u32 s98, s96, s100
	s_addc_u32 s99, s97, 0
	s_lshl_b32 s100, s30, 9
	s_add_u32 s98, s98, s100
	s_addc_u32 s99, s99, 0
	v_mbcnt_lo_u32_b32 v250, -1, 0
	v_mbcnt_hi_u32_b32 v250, -1, v250
	s_lshr_b32 s100, s31, 10
	v_lshl_or_b32 v250, s100, 6, v250
	v_lshrrev_b32_e32 v251, 2, v250
	v_and_b32_e32 v250, 3, v250
	v_lshlrev_b32_e32 v250, 7, v250
	v_mul_u32_u24_e32 v251, 0x2080, v251
	v_add_u32_e32 v250, v251, v250
	global_load_dword v251, v250, s[98:99]
	s_add_u32 s98, s98, 0x104000
	s_addc_u32 s99, s99, 0
	global_load_dword v251, v250, s[98:99]

	.amdhsa_kernel _Z6mk_fwd4Args
		.amdhsa_group_segment_fixed_size 0
		.amdhsa_private_segment_fixed_size 0
		.amdhsa_kernarg_size 456
		.amdhsa_user_sgpr_count 2
		.amdhsa_user_sgpr_dispatch_ptr 0
		.amdhsa_user_sgpr_queue_ptr 0
		.amdhsa_user_sgpr_kernarg_segment_ptr 1
		.amdhsa_user_sgpr_dispatch_id 0
		.amdhsa_user_sgpr_kernarg_preload_length 0
		.amdhsa_user_sgpr_kernarg_preload_offset 0
		.amdhsa_user_sgpr_private_segment_size 0
		.amdhsa_uses_dynamic_stack 0
		.amdhsa_enable_private_segment 0
		.amdhsa_system_sgpr_workgroup_id_x 1
		.amdhsa_system_sgpr_workgroup_id_y 0
		.amdhsa_system_sgpr_workgroup_id_z 0
		.amdhsa_system_sgpr_workgroup_info 0
		.amdhsa_system_vgpr_workitem_id 0
		.amdhsa_next_free_vgpr 252
		.amdhsa_next_free_sgpr 102
		.amdhsa_accum_offset 252
		.amdhsa_reserve_vcc 1
		.amdhsa_float_round_mode_32 0
		.amdhsa_float_round_mode_16_64 0
		.amdhsa_float_denorm_mode_32 3
		.amdhsa_float_denorm_mode_16_64 3
		.amdhsa_dx10_clamp 1
		.amdhsa_ieee_mode 1
		.amdhsa_fp16_overflow 0
		.amdhsa_tg_split 0
		.amdhsa_exception_fp_ieee_invalid_op 0
		.amdhsa_exception_fp_denorm_src 0
		.amdhsa_exception_fp_ieee_div_zero 0
		.amdhsa_exception_fp_ieee_overflow 0
		.amdhsa_exception_fp_ieee_underflow 0
		.amdhsa_exception_fp_ieee_inexact 0
		.amdhsa_exception_int_div_zero 0
	.end_amdhsa_kernel

amdhsa.kernels:
  - .agpr_count:     0
    .args:
      - .offset:         0
        .size:           200
        .value_kind:     by_value
      - .offset:         200
        .size:           4
        .value_kind:     hidden_block_count_x
      - .offset:         204
        .size:           4
        .value_kind:     hidden_block_count_y
      - .offset:         208
        .size:           4
        .value_kind:     hidden_block_count_z
      - .offset:         212
        .size:           2
        .value_kind:     hidden_group_size_x
      - .offset:         214
        .size:           2
        .value_kind:     hidden_group_size_y
      - .offset:         216
        .size:           2
        .value_kind:     hidden_group_size_z
      - .offset:         218
        .size:           2
        .value_kind:     hidden_remainder_x
      - .offset:         220
        .size:           2
        .value_kind:     hidden_remainder_y
      - .offset:         222
        .size:           2
        .value_kind:     hidden_remainder_z
      - .offset:         240
        .size:           8
        .value_kind:     hidden_global_offset_x
      - .offset:         248
        .size:           8
        .value_kind:     hidden_global_offset_y
      - .offset:         256
        .size:           8
        .value_kind:     hidden_global_offset_z
      - .offset:         264
        .size:           2
        .value_kind:     hidden_grid_dims
      - .offset:         320
        .size:           4
        .value_kind:     hidden_dynamic_lds_size
    .group_segment_fixed_size: 0
    .kernarg_segment_align: 8
    .kernarg_segment_size: 456
    .language:       OpenCL C
    .language_version:
      - 2
      - 0
    .max_flat_workgroup_size: 512
    .name:           _Z6mk_fwd4Args
    .private_segment_fixed_size: 0
    .sgpr_count:     108
    .sgpr_spill_count: 79
    .symbol:         _Z6mk_fwd4Args.kd
    .uniform_work_group_size: 1
    .uses_dynamic_stack: false
    .vgpr_count:     252
    .vgpr_spill_count: 0
    .wavefront_size: 64
